# grid barrier: every workgroup polls the TOP arrival counter directly (no TOPGEN/XGEN hand-off hops), on top of v8
# speedup vs baseline: 1.0496x; 1.0044x over previous
; DI unsigned xb_ld(unsigned* p)              { return __hip_atomic_load(p, __ATOMIC_RELAXED, __HIP_MEMORY_SCOPE_AGENT); }
; DI unsigned xb_add(unsigned* p, unsigned v) { return __hip_atomic_fetch_add(p, v, __ATOMIC_RELAXED, __HIP_MEMORY_SCOPE_AGENT); }
; #define XB_SPIN(cond, bar) do { unsigned _sp = 0; while (cond) { __builtin_amdgcn_s_sleep(1); \
;     if ((++_sp & 255u) == 0u) { if (xb_ld(&(bar)[XB_TMO])) break; if (_sp > XB_SPIN_CAP) { atomicAdd(&(bar)[XB_TMO], 1u); break; } } } } while (0)
; DI void xcd_barrier(const XcdBarrier& b) {
;     ...
;         const unsigned old = xb_add(&bar[XB_XSUB(b.x)], 1u);
;         const unsigned gen = old / nloc;
;         if (old + 1u == (gen + 1u) * nloc) {
;             __builtin_amdgcn_fence(__ATOMIC_RELEASE, "agent");
;             asm volatile("s_waitcnt vmcnt(0)" ::: "memory");
;             const unsigned og = xb_add(&bar[XB_TOP], 1u);
;             const unsigned tg = og / nx;
;             if (og + 1u == (tg + 1u) * nx) xb_add(&bar[XB_TOPGEN], 1u);
;             else XB_SPIN(xb_ld(&bar[XB_TOPGEN]) == tg, bar);
;             __builtin_amdgcn_fence(__ATOMIC_ACQUIRE, "agent");
;             xb_add(&bar[XB_XGEN(b.x)], 1u);
;             asm volatile("s_waitcnt vmcnt(0)" ::: "memory");
;         } else {
;             XB_SPIN(xb_ld(&bar[XB_XGEN(b.x)]) == gen, bar);
;             __builtin_amdgcn_fence(__ATOMIC_ACQUIRE, "agent");
;             asm volatile("s_waitcnt vmcnt(0)" ::: "memory");
;         }
.LBB0_87:
	s_lshl_b32 s0, s96, 8
	v_mov_b32_e32 v0, s0
	v_add_u32_e32 v0, 0x1000, v0
	v_mov_b32_e32 v3, 1
	global_atomic_add v3, v0, v3, s[68:69] offset:1024 sc0
	s_waitcnt lgkmcnt(0)
	v_cvt_f32_u32_e32 v0, v2
	v_sub_u32_e32 v4, 0, v2
	v_rcp_iflag_f32_e32 v0, v0
	s_nop 0
	v_mul_f32_e32 v0, 0x4f7ffffe, v0
	v_cvt_u32_f32_e32 v0, v0
	v_mul_lo_u32 v4, v4, v0
	v_mul_hi_u32 v4, v0, v4
	v_add_u32_e32 v0, v0, v4
	s_waitcnt vmcnt(0)
	v_mul_hi_u32 v0, v3, v0
	v_mul_lo_u32 v4, v0, v2
	v_sub_u32_e32 v4, v3, v4
	v_add_u32_e32 v5, 1, v0
	v_cmp_ge_u32_e32 vcc, v4, v2
	v_add_u32_e32 v3, 1, v3
	s_nop 0
	v_cndmask_b32_e32 v0, v0, v5, vcc
	v_sub_u32_e32 v5, v4, v2
	v_cndmask_b32_e32 v4, v4, v5, vcc
	v_add_u32_e32 v5, 1, v0
	v_cmp_ge_u32_e32 vcc, v4, v2
	s_nop 1
	v_cndmask_b32_e32 v0, v0, v5, vcc
	v_mul_lo_u32 v4, v2, v0
	v_add_u32_e32 v2, v4, v2
	v_cmp_ne_u32_e32 vcc, v3, v2
	v_add_u32_e32 v5, 1, v0
	v_mul_lo_u32 v5, v5, v1
	v_mov_b32_e32 v4, 0x3000
	s_cbranch_vccnz .Lxb0_poll
	buffer_wbl2 sc1
	s_waitcnt vmcnt(0) lgkmcnt(0)
	v_mov_b32_e32 v3, 1
	global_atomic_add v4, v3, s[68:69] offset:1024
.Lxb0_poll:
	s_mov_b32 s1, 0
.Lxb0_spin:
	global_load_dword v3, v4, s[68:69] offset:1024 sc1
	s_waitcnt vmcnt(0)
	v_cmp_lt_u32_e32 vcc, v3, v5
	s_cbranch_vccz .Lxb0_done
	s_sleep 1
	s_add_i32 s1, s1, 1
	s_cmp_lt_u32 s1, 0x40000
	s_cbranch_scc1 .Lxb0_spin
.Lxb0_done:
	buffer_inv sc1
	s_waitcnt vmcnt(0)
